# instruction selection: 8 of 16 LDS-DMA loads per UP K-loop iteration use SGPR base + 32-bit VGPR offset addressing, removing their 64-bit VALU address adds from the load segment; otherwise as v71
# speedup vs baseline: 1.0081x; 1.0081x over previous
.LBB0_692:
	s_add_u32 s20, s40, 0xfffc0080
	s_addc_u32 s21, s41, -1
	s_add_i32 s71, 0, 0x10000
	s_cmp_eq_u32 s70, 12
	s_cselect_b32 s51, s43, s21
	s_cselect_b32 s50, s66, s20
	s_cselect_b32 s21, s19, s69
	s_cselect_b32 s20, s67, s68
	s_add_i32 s74, 0, 0x14000
	v_add_u32_e32 v150, s71, v156
	v_add_u32_e32 v188, s74, v156
	ds_read_b128 v[138:141], v150
	ds_read_b128 v[142:145], v150 offset:1024
	ds_read_b128 v[146:149], v150 offset:2048
	ds_read_b128 v[150:153], v150 offset:3072
	ds_read_b128 v[176:179], v188
	ds_read_b128 v[180:183], v188 offset:1024
	ds_read_b128 v[184:187], v188 offset:2048
	ds_read_b128 v[188:191], v188 offset:3072
	s_add_i32 m0, s57, 0xc000
	ds_read_b128 v[192:195], v175
	ds_read_b128 v[196:199], v175 offset:1024
	ds_read_b128 v[200:203], v175 offset:2048
	ds_read_b128 v[204:207], v175 offset:3072
	ds_read_b128 v[208:211], v175 offset:4096
	ds_read_b128 v[212:215], v175 offset:5120
	ds_read_b128 v[216:219], v175 offset:6144
	ds_read_b128 v[220:223], v175 offset:7168
	global_load_lds_dwordx4 v136, s[40:41]
	s_add_i32 m0, s57, 0xe000
	s_nop 0
	global_load_lds_dwordx4 v134, s[40:41]
	s_waitcnt vmcnt(8)
	s_waitcnt lgkmcnt(0)
	s_setprio 1
	s_barrier
	v_mfma_f32_16x16x32_bf16 v[124:127], v[138:141], v[192:195], v[124:127]
	v_mfma_f32_16x16x32_bf16 v[124:127], v[142:145], v[196:199], v[124:127]
	v_mfma_f32_16x16x32_bf16 v[112:115], v[146:149], v[192:195], v[112:115]
	v_mfma_f32_16x16x32_bf16 v[112:115], v[150:153], v[196:199], v[112:115]
	v_mfma_f32_16x16x32_bf16 v[108:111], v[138:141], v[200:203], v[108:111]
	v_mfma_f32_16x16x32_bf16 v[108:111], v[142:145], v[204:207], v[108:111]
	v_mfma_f32_16x16x32_bf16 v[96:99], v[146:149], v[200:203], v[96:99]
	v_mfma_f32_16x16x32_bf16 v[96:99], v[150:153], v[204:207], v[96:99]
	v_mfma_f32_16x16x32_bf16 v[92:95], v[138:141], v[208:211], v[92:95]
	v_mfma_f32_16x16x32_bf16 v[92:95], v[142:145], v[212:215], v[92:95]
	v_mfma_f32_16x16x32_bf16 v[80:83], v[146:149], v[208:211], v[80:83]
	v_mfma_f32_16x16x32_bf16 v[80:83], v[150:153], v[212:215], v[80:83]
	v_mfma_f32_16x16x32_bf16 v[76:79], v[138:141], v[216:219], v[76:79]
	v_mfma_f32_16x16x32_bf16 v[76:79], v[142:145], v[220:223], v[76:79]
	v_mfma_f32_16x16x32_bf16 v[64:67], v[146:149], v[216:219], v[64:67]
	v_mfma_f32_16x16x32_bf16 v[64:67], v[150:153], v[220:223], v[64:67]
	v_mfma_f32_16x16x32_bf16 v[120:123], v[176:179], v[192:195], v[120:123]
	v_mfma_f32_16x16x32_bf16 v[120:123], v[180:183], v[196:199], v[120:123]
	v_mfma_f32_16x16x32_bf16 v[116:119], v[184:187], v[192:195], v[116:119]
	v_mfma_f32_16x16x32_bf16 v[116:119], v[188:191], v[196:199], v[116:119]
	v_mfma_f32_16x16x32_bf16 v[104:107], v[176:179], v[200:203], v[104:107]
	v_mfma_f32_16x16x32_bf16 v[104:107], v[180:183], v[204:207], v[104:107]
	v_mfma_f32_16x16x32_bf16 v[100:103], v[184:187], v[200:203], v[100:103]
	v_mfma_f32_16x16x32_bf16 v[100:103], v[188:191], v[204:207], v[100:103]
	v_mfma_f32_16x16x32_bf16 v[88:91], v[176:179], v[208:211], v[88:91]
	v_mfma_f32_16x16x32_bf16 v[88:91], v[180:183], v[212:215], v[88:91]
	v_mfma_f32_16x16x32_bf16 v[84:87], v[184:187], v[208:211], v[84:87]
	v_mfma_f32_16x16x32_bf16 v[84:87], v[188:191], v[212:215], v[84:87]
	v_mfma_f32_16x16x32_bf16 v[72:75], v[176:179], v[216:219], v[72:75]
	v_mfma_f32_16x16x32_bf16 v[72:75], v[180:183], v[220:223], v[72:75]
	v_mfma_f32_16x16x32_bf16 v[68:71], v[184:187], v[216:219], v[68:71]
	v_mfma_f32_16x16x32_bf16 v[68:71], v[188:191], v[220:223], v[68:71]
	s_barrier
	s_setprio 0
	s_add_i32 s71, s71, s54
	v_lshl_add_u64 v[224:225], s[20:21], 0, v[168:169]
	s_mov_b32 m0, s71
	ds_read_b128 v[192:195], v175 offset:16384
	ds_read_b128 v[196:199], v175 offset:17408
	ds_read_b128 v[200:203], v175 offset:18432
	ds_read_b128 v[204:207], v175 offset:19456
	ds_read_b128 v[208:211], v175 offset:20480
	ds_read_b128 v[212:215], v175 offset:21504
	ds_read_b128 v[216:219], v175 offset:22528
	ds_read_b128 v[220:223], v175 offset:23552
	global_load_lds_dwordx4 v[224:225], off
	s_add_i32 m0, s71, 0x2000
	s_add_u32 s72, s20, 0x40000
	v_lshl_add_u64 v[226:227], s[20:21], 0, v[128:129]
	s_addc_u32 s73, s21, 0
	s_add_i32 s71, s74, s54
	global_load_lds_dwordx4 v[226:227], off
	s_mov_b32 m0, s71
	v_lshl_add_u64 v[230:231], s[50:51], 0, v[130:131]
	global_load_lds_dwordx4 v168, s[72:73]
	s_add_i32 m0, s71, 0x2000
	s_nop 0
	global_load_lds_dwordx4 v128, s[72:73]
	v_lshl_add_u64 v[228:229], s[50:51], 0, v[132:133]
	s_mov_b32 m0, s57
	s_nop 0
	global_load_lds_dwordx4 v[228:229], off
	s_mov_b32 m0, s58
	s_nop 0
	global_load_lds_dwordx4 v[230:231], off
	s_waitcnt vmcnt(8)
	s_waitcnt lgkmcnt(0)
	s_setprio 1
	s_barrier
	v_mfma_f32_16x16x32_bf16 v[60:63], v[138:141], v[192:195], v[60:63]
	v_mfma_f32_16x16x32_bf16 v[60:63], v[142:145], v[196:199], v[60:63]
	v_mfma_f32_16x16x32_bf16 v[48:51], v[146:149], v[192:195], v[48:51]
	v_mfma_f32_16x16x32_bf16 v[48:51], v[150:153], v[196:199], v[48:51]
	v_mfma_f32_16x16x32_bf16 v[44:47], v[138:141], v[200:203], v[44:47]
	v_mfma_f32_16x16x32_bf16 v[44:47], v[142:145], v[204:207], v[44:47]
	v_mfma_f32_16x16x32_bf16 v[32:35], v[146:149], v[200:203], v[32:35]
	v_mfma_f32_16x16x32_bf16 v[32:35], v[150:153], v[204:207], v[32:35]
	v_mfma_f32_16x16x32_bf16 v[28:31], v[138:141], v[208:211], v[28:31]
	v_mfma_f32_16x16x32_bf16 v[28:31], v[142:145], v[212:215], v[28:31]
	v_mfma_f32_16x16x32_bf16 v[16:19], v[146:149], v[208:211], v[16:19]
	v_mfma_f32_16x16x32_bf16 v[16:19], v[150:153], v[212:215], v[16:19]
	v_mfma_f32_16x16x32_bf16 v[12:15], v[138:141], v[216:219], v[12:15]
	v_mfma_f32_16x16x32_bf16 v[12:15], v[142:145], v[220:223], v[12:15]
	v_mfma_f32_16x16x32_bf16 v[4:7], v[146:149], v[216:219], v[4:7]
	v_mfma_f32_16x16x32_bf16 v[4:7], v[150:153], v[220:223], v[4:7]
	v_mfma_f32_16x16x32_bf16 v[56:59], v[176:179], v[192:195], v[56:59]
	v_mfma_f32_16x16x32_bf16 v[56:59], v[180:183], v[196:199], v[56:59]
	v_mfma_f32_16x16x32_bf16 v[52:55], v[184:187], v[192:195], v[52:55]
	v_mfma_f32_16x16x32_bf16 v[52:55], v[188:191], v[196:199], v[52:55]
	v_mfma_f32_16x16x32_bf16 v[40:43], v[176:179], v[200:203], v[40:43]
	v_mfma_f32_16x16x32_bf16 v[40:43], v[180:183], v[204:207], v[40:43]
	v_mfma_f32_16x16x32_bf16 v[36:39], v[184:187], v[200:203], v[36:39]
	v_mfma_f32_16x16x32_bf16 v[36:39], v[188:191], v[204:207], v[36:39]
	v_mfma_f32_16x16x32_bf16 v[24:27], v[176:179], v[208:211], v[24:27]
	v_mfma_f32_16x16x32_bf16 v[24:27], v[180:183], v[212:215], v[24:27]
	v_mfma_f32_16x16x32_bf16 v[20:23], v[184:187], v[208:211], v[20:23]
	v_mfma_f32_16x16x32_bf16 v[20:23], v[188:191], v[212:215], v[20:23]
	v_mfma_f32_16x16x32_bf16 v[8:11], v[176:179], v[216:219], v[8:11]
	v_mfma_f32_16x16x32_bf16 v[8:11], v[180:183], v[220:223], v[8:11]
	v_mfma_f32_16x16x32_bf16 v[0:3], v[184:187], v[216:219], v[0:3]
	v_mfma_f32_16x16x32_bf16 v[0:3], v[188:191], v[220:223], v[0:3]
	s_barrier
	s_setprio 0
	s_add_i32 s71, 0, 0x18000
	s_add_i32 s72, 0, 0x1c000
	v_add_u32_e32 v150, s71, v156
	v_add_u32_e32 v188, s72, v156
	ds_read_b128 v[138:141], v150
	ds_read_b128 v[142:145], v150 offset:1024
	ds_read_b128 v[146:149], v150 offset:2048
	ds_read_b128 v[150:153], v150 offset:3072
	ds_read_b128 v[176:179], v188
	ds_read_b128 v[180:183], v188 offset:1024
	ds_read_b128 v[184:187], v188 offset:2048
	ds_read_b128 v[188:191], v188 offset:3072
	s_add_u32 s50, s50, 0x40000
	s_addc_u32 s51, s51, 0
	s_mov_b32 m0, s59
	ds_read_b128 v[192:195], v175 offset:32768
	ds_read_b128 v[196:199], v175 offset:33792
	ds_read_b128 v[200:203], v175 offset:34816
	ds_read_b128 v[204:207], v175 offset:35840
	ds_read_b128 v[208:211], v175 offset:36864
	ds_read_b128 v[212:215], v175 offset:37888
	ds_read_b128 v[216:219], v175 offset:38912
	ds_read_b128 v[220:223], v175 offset:39936
	global_load_lds_dwordx4 v132, s[50:51]
	s_mov_b32 m0, s60
	s_nop 0
	global_load_lds_dwordx4 v130, s[50:51]
	s_waitcnt vmcnt(8)
	s_waitcnt lgkmcnt(0)
	s_setprio 1
	s_barrier
	v_mfma_f32_16x16x32_bf16 v[124:127], v[138:141], v[192:195], v[124:127]
	v_mfma_f32_16x16x32_bf16 v[124:127], v[142:145], v[196:199], v[124:127]
	v_mfma_f32_16x16x32_bf16 v[112:115], v[146:149], v[192:195], v[112:115]
	v_mfma_f32_16x16x32_bf16 v[112:115], v[150:153], v[196:199], v[112:115]
	v_mfma_f32_16x16x32_bf16 v[108:111], v[138:141], v[200:203], v[108:111]
	v_mfma_f32_16x16x32_bf16 v[108:111], v[142:145], v[204:207], v[108:111]
	v_mfma_f32_16x16x32_bf16 v[96:99], v[146:149], v[200:203], v[96:99]
	v_mfma_f32_16x16x32_bf16 v[96:99], v[150:153], v[204:207], v[96:99]
	v_mfma_f32_16x16x32_bf16 v[92:95], v[138:141], v[208:211], v[92:95]
	v_mfma_f32_16x16x32_bf16 v[92:95], v[142:145], v[212:215], v[92:95]
	v_mfma_f32_16x16x32_bf16 v[80:83], v[146:149], v[208:211], v[80:83]
	v_mfma_f32_16x16x32_bf16 v[80:83], v[150:153], v[212:215], v[80:83]
	v_mfma_f32_16x16x32_bf16 v[76:79], v[138:141], v[216:219], v[76:79]
	v_mfma_f32_16x16x32_bf16 v[76:79], v[142:145], v[220:223], v[76:79]
	v_mfma_f32_16x16x32_bf16 v[64:67], v[146:149], v[216:219], v[64:67]
	v_mfma_f32_16x16x32_bf16 v[64:67], v[150:153], v[220:223], v[64:67]
	v_mfma_f32_16x16x32_bf16 v[120:123], v[176:179], v[192:195], v[120:123]
	v_mfma_f32_16x16x32_bf16 v[120:123], v[180:183], v[196:199], v[120:123]
	v_mfma_f32_16x16x32_bf16 v[116:119], v[184:187], v[192:195], v[116:119]
	v_mfma_f32_16x16x32_bf16 v[116:119], v[188:191], v[196:199], v[116:119]
	v_mfma_f32_16x16x32_bf16 v[104:107], v[176:179], v[200:203], v[104:107]
	v_mfma_f32_16x16x32_bf16 v[104:107], v[180:183], v[204:207], v[104:107]
	v_mfma_f32_16x16x32_bf16 v[100:103], v[184:187], v[200:203], v[100:103]
	v_mfma_f32_16x16x32_bf16 v[100:103], v[188:191], v[204:207], v[100:103]
	v_mfma_f32_16x16x32_bf16 v[88:91], v[176:179], v[208:211], v[88:91]
	v_mfma_f32_16x16x32_bf16 v[88:91], v[180:183], v[212:215], v[88:91]
	v_mfma_f32_16x16x32_bf16 v[84:87], v[184:187], v[208:211], v[84:87]
	v_mfma_f32_16x16x32_bf16 v[84:87], v[188:191], v[212:215], v[84:87]
	v_mfma_f32_16x16x32_bf16 v[72:75], v[176:179], v[216:219], v[72:75]
	v_mfma_f32_16x16x32_bf16 v[72:75], v[180:183], v[220:223], v[72:75]
	v_mfma_f32_16x16x32_bf16 v[68:71], v[184:187], v[216:219], v[68:71]
	v_mfma_f32_16x16x32_bf16 v[68:71], v[188:191], v[220:223], v[68:71]
	s_barrier
	s_setprio 0
	s_add_i32 s50, s71, s54
	v_lshl_add_u64 v[224:225], v[224:225], 0, s[36:37]
	s_mov_b32 m0, s50
	ds_read_b128 v[192:195], v175 offset:49152
	ds_read_b128 v[196:199], v175 offset:50176
	ds_read_b128 v[200:203], v175 offset:51200
	ds_read_b128 v[204:207], v175 offset:52224
	ds_read_b128 v[208:211], v175 offset:53248
	ds_read_b128 v[212:215], v175 offset:54272
	ds_read_b128 v[216:219], v175 offset:55296
	ds_read_b128 v[220:223], v175 offset:56320
	global_load_lds_dwordx4 v[224:225], off
	s_add_i32 m0, s50, 0x2000
	s_add_u32 s20, s20, 0x40080
	v_lshl_add_u64 v[224:225], v[226:227], 0, s[36:37]
	s_addc_u32 s21, s21, 0
	s_add_i32 s50, s72, s54
	global_load_lds_dwordx4 v[224:225], off
	s_mov_b32 m0, s50
	s_nop 0
	global_load_lds_dwordx4 v168, s[20:21]
	s_add_i32 m0, s50, 0x2000
	s_nop 0
	global_load_lds_dwordx4 v128, s[20:21]
	v_lshl_add_u64 v[224:225], v[228:229], 0, s[36:37]
	s_mov_b32 m0, s61
	s_nop 0
	global_load_lds_dwordx4 v[224:225], off
	v_lshl_add_u64 v[224:225], v[230:231], 0, s[36:37]
	s_mov_b32 m0, s62
	s_nop 0
	global_load_lds_dwordx4 v[224:225], off
	s_waitcnt vmcnt(8)
	s_waitcnt lgkmcnt(0)
	s_setprio 1
	s_barrier
	v_mfma_f32_16x16x32_bf16 v[60:63], v[138:141], v[192:195], v[60:63]
	v_mfma_f32_16x16x32_bf16 v[60:63], v[142:145], v[196:199], v[60:63]
	v_mfma_f32_16x16x32_bf16 v[48:51], v[146:149], v[192:195], v[48:51]
	v_mfma_f32_16x16x32_bf16 v[48:51], v[150:153], v[196:199], v[48:51]
	v_mfma_f32_16x16x32_bf16 v[44:47], v[138:141], v[200:203], v[44:47]
	v_mfma_f32_16x16x32_bf16 v[44:47], v[142:145], v[204:207], v[44:47]
	v_mfma_f32_16x16x32_bf16 v[32:35], v[146:149], v[200:203], v[32:35]
	v_mfma_f32_16x16x32_bf16 v[32:35], v[150:153], v[204:207], v[32:35]
	v_mfma_f32_16x16x32_bf16 v[28:31], v[138:141], v[208:211], v[28:31]
	v_mfma_f32_16x16x32_bf16 v[28:31], v[142:145], v[212:215], v[28:31]
	v_mfma_f32_16x16x32_bf16 v[16:19], v[146:149], v[208:211], v[16:19]
	v_mfma_f32_16x16x32_bf16 v[16:19], v[150:153], v[212:215], v[16:19]
	v_mfma_f32_16x16x32_bf16 v[12:15], v[138:141], v[216:219], v[12:15]
	v_mfma_f32_16x16x32_bf16 v[12:15], v[142:145], v[220:223], v[12:15]
	v_mfma_f32_16x16x32_bf16 v[4:7], v[146:149], v[216:219], v[4:7]
	v_mfma_f32_16x16x32_bf16 v[4:7], v[150:153], v[220:223], v[4:7]
	v_mfma_f32_16x16x32_bf16 v[56:59], v[176:179], v[192:195], v[56:59]
	v_mfma_f32_16x16x32_bf16 v[56:59], v[180:183], v[196:199], v[56:59]
	v_mfma_f32_16x16x32_bf16 v[52:55], v[184:187], v[192:195], v[52:55]
	v_mfma_f32_16x16x32_bf16 v[52:55], v[188:191], v[196:199], v[52:55]
	v_mfma_f32_16x16x32_bf16 v[40:43], v[176:179], v[200:203], v[40:43]
	v_mfma_f32_16x16x32_bf16 v[40:43], v[180:183], v[204:207], v[40:43]
	v_mfma_f32_16x16x32_bf16 v[36:39], v[184:187], v[200:203], v[36:39]
	v_mfma_f32_16x16x32_bf16 v[36:39], v[188:191], v[204:207], v[36:39]
	v_mfma_f32_16x16x32_bf16 v[24:27], v[176:179], v[208:211], v[24:27]
	v_mfma_f32_16x16x32_bf16 v[24:27], v[180:183], v[212:215], v[24:27]
	v_mfma_f32_16x16x32_bf16 v[20:23], v[184:187], v[208:211], v[20:23]
	v_mfma_f32_16x16x32_bf16 v[20:23], v[188:191], v[212:215], v[20:23]
	v_mfma_f32_16x16x32_bf16 v[8:11], v[176:179], v[216:219], v[8:11]
	v_mfma_f32_16x16x32_bf16 v[8:11], v[180:183], v[220:223], v[8:11]
	v_mfma_f32_16x16x32_bf16 v[0:3], v[184:187], v[216:219], v[0:3]
	v_mfma_f32_16x16x32_bf16 v[0:3], v[188:191], v[220:223], v[0:3]
	s_barrier
	s_setprio 0
	s_add_i32 s70, s70, 2
	s_add_u32 s68, s68, 0x100
	s_addc_u32 s69, s69, 0
	s_add_u32 s40, s40, 0x100
	s_addc_u32 s41, s41, 0
	s_cmp_gt_u32 s70, 13
	s_cbranch_scc0 .LBB0_692
	s_and_b64 vcc, exec, s[16:17]
	s_cbranch_vccz .LBB0_695
	s_barrier
